# attention: first K-fragment LDS reads hoisted above the K/V staging block (on top of v7)
# baseline (speedup 1.0000x reference)
.Latt_prio_done:
.LBB0_674:
	s_add_i32 s70, s67, 1
	s_and_b32 s69, s70, 3
	s_mul_i32 s2, s69, 0x3400
	v_add_u32_e32 v0, s2, v196
	ds_read_b128 v[2:5], v0
	ds_read_b128 v[6:9], v0 offset:6656
	s_add_i32 s2, s67, -1
	s_and_b32 s2, s2, 3
	s_mulk_i32 s2, 0x3400
	s_and_b32 s71, s67, 2
	s_add_i32 s2, s2, 0
	s_xor_b32 s3, s71, 2
	v_add_u32_e32 v96, s2, v192
	s_mulk_i32 s3, 0x2400
	s_waitcnt vmcnt(5)
	ds_write_b128 v96, v[152:155]
	v_add_u32_e32 v96, s2, v185
	s_add_i32 s2, s67, 5
	s_waitcnt vmcnt(4)
	ds_write_b128 v96, v[156:159] offset:128
	v_add_u32_e32 v96, s3, v193
	s_min_i32 s46, s2, s66
	s_add_i32 s2, s67, 4
	v_add_u32_e32 v96, 0xd000, v96
	s_min_i32 s2, s2, s66
	s_lshl_b64 s[4:5], s[46:47], 16
	s_mov_b32 s3, s47
	s_waitcnt vmcnt(3)
	ds_write2_b64 v96, v[172:173], v[174:175] offset1:2
	v_lshl_add_u64 v[98:99], v[186:187], 0, s[4:5]
	s_lshl_b64 s[4:5], s[46:47], 12
	s_lshl_b64 s[2:3], s[2:3], 7
	v_lshl_add_u64 v[100:101], v[188:189], 0, s[4:5]
	global_load_dwordx4 v[152:155], v[98:99], off
	global_load_dwordx4 v[156:159], v[100:101], off
	v_lshl_add_u64 v[98:99], v[190:191], 0, s[2:3]
	global_load_dwordx4 v[172:175], v[98:99], off
	s_cmp_gt_i32 s67, s65
	s_cbranch_scc1 .LBB0_685
	s_waitcnt lgkmcnt(1)
	v_mfma_f32_32x32x16_bf16 v[112:127], v[2:5], v[128:131], v[48:63]
	ds_read_b128 v[10:13], v0 offset:32
	ds_read_b128 v[202:205], v0 offset:6688
	v_add_f32_e32 v14, 0, v80
	v_add_f32_e32 v14, v81, v14
	v_cvt_pk_bf16_f32 v176, v80, v81
	s_waitcnt lgkmcnt(2)
	v_mfma_f32_32x32x16_bf16 v[96:111], v[6:9], v[128:131], v[48:63]
	v_add_f32_e32 v2, v82, v14
	v_add_f32_e32 v2, v83, v2
	v_add_f32_e32 v14, v84, v2
	v_cvt_pk_bf16_f32 v177, v82, v83
	s_waitcnt lgkmcnt(1)
	v_mfma_f32_32x32x16_bf16 v[112:127], v[10:13], v[132:135], v[112:127]
	ds_read_b128 v[2:5], v0 offset:64
	ds_read_b128 v[6:9], v0 offset:6720
	v_add_f32_e32 v14, v85, v14
	v_add_f32_e32 v14, v86, v14
	v_add_f32_e32 v14, v87, v14
	v_cvt_pk_bf16_f32 v178, v84, v85
	v_cvt_pk_bf16_f32 v179, v86, v87
	s_waitcnt lgkmcnt(2)
	v_mfma_f32_32x32x16_bf16 v[96:111], v[202:205], v[132:135], v[96:111]
	v_add_f32_e32 v10, v88, v14
	v_add_f32_e32 v11, v89, v10
	v_cvt_pk_bf16_f32 v10, v88, v89
	s_waitcnt lgkmcnt(1)
	v_mfma_f32_32x32x16_bf16 v[112:127], v[2:5], v[136:139], v[112:127]
	ds_read_b128 v[80:83], v0 offset:96
	ds_read_b128 v[202:205], v0 offset:6752
	v_add_f32_e32 v11, v90, v11
	v_add_f32_e32 v11, v91, v11
	v_add_f32_e32 v12, v92, v11
	v_cvt_pk_bf16_f32 v11, v90, v91
	s_waitcnt lgkmcnt(2)
	v_mfma_f32_32x32x16_bf16 v[96:111], v[6:9], v[136:139], v[96:111]
	v_add_f32_e32 v2, v93, v12
	v_add_f32_e32 v2, v94, v2
	v_add_f32_e32 v14, v95, v2
	v_cvt_pk_bf16_f32 v12, v92, v93
	v_cvt_pk_bf16_f32 v13, v94, v95
	s_waitcnt lgkmcnt(1)
	v_mfma_f32_32x32x16_bf16 v[112:127], v[80:83], v[140:143], v[112:127]
	ds_read_b128 v[2:5], v0 offset:128
	ds_read_b128 v[206:209], v0 offset:6784
	v_add_f32_e32 v6, v16, v14
	v_add_f32_e32 v7, v17, v6
	v_cvt_pk_bf16_f32 v6, v16, v17
	s_waitcnt lgkmcnt(2)
	v_mfma_f32_32x32x16_bf16 v[96:111], v[202:205], v[140:143], v[96:111]
	v_add_f32_e32 v7, v18, v7
	v_add_f32_e32 v7, v19, v7
	v_add_f32_e32 v8, v20, v7
	v_cvt_pk_bf16_f32 v7, v18, v19
	s_waitcnt lgkmcnt(1)
	v_mfma_f32_32x32x16_bf16 v[112:127], v[2:5], v[144:147], v[112:127]
	ds_read_b128 v[14:17], v0 offset:160
	ds_read_b128 v[80:83], v0 offset:6816
	v_add_f32_e32 v0, v21, v8
	v_add_f32_e32 v0, v22, v0
	v_add_f32_e32 v0, v23, v0
	v_cvt_pk_bf16_f32 v8, v20, v21
	v_cvt_pk_bf16_f32 v9, v22, v23
	s_waitcnt lgkmcnt(2)
	v_mfma_f32_32x32x16_bf16 v[96:111], v[206:209], v[144:147], v[96:111]
	v_add_f32_e32 v0, v24, v0
	v_add_f32_e32 v0, v25, v0
	v_cvt_pk_bf16_f32 v2, v24, v25
	s_waitcnt lgkmcnt(1)
	v_mfma_f32_32x32x16_bf16 v[112:127], v[14:17], v[148:151], v[112:127]
	v_add_f32_e32 v0, v26, v0
	v_add_f32_e32 v0, v27, v0
	v_add_f32_e32 v0, v28, v0
	v_cvt_pk_bf16_f32 v3, v26, v27
	s_waitcnt lgkmcnt(0)
	v_mfma_f32_32x32x16_bf16 v[96:111], v[80:83], v[148:151], v[96:111]
	v_add_f32_e32 v0, v29, v0
	v_add_f32_e32 v0, v30, v0
	v_add_f32_e32 v0, v31, v0
	v_cvt_pk_bf16_f32 v4, v28, v29
	v_cvt_pk_bf16_f32 v5, v30, v31
	s_mul_i32 s4, s71, 0x2400
	v_add_u32_e32 v206, s4, v200
	ds_read_b128 v[16:19], v206 offset:53248
	ds_read_b128 v[202:205], v206 offset:57856
	s_cmp_ge_i32 s67, s65
	v_add_f32_e32 v201, v201, v0
	s_cbranch_scc1 .LBB0_682
	s_sub_i32 s2, s68, 64
	s_cmp_le_i32 s2, s63
	s_cbranch_scc1 .LBB0_680
	v_add_u32_e32 v0, s68, v197
	v_add_u32_e32 v15, 0xffffffa1, v0
	v_add_u32_e32 v14, 0xffffff81, v0
	v_cmp_le_i32_e64 s[2:3], v15, v184
	v_cmp_le_i32_e32 vcc, v14, v184
	s_nop 0
	v_cndmask_b32_e64 v96, v194, v96, s[2:3]
	v_cmp_lt_i32_e64 s[2:3], v14, v184
	v_add_u32_e32 v14, 0xffffffa2, v0
	v_cmp_le_i32_e64 s[4:5], v14, v184
	v_add_u32_e32 v14, 0xffffff83, v0
	s_nop 0
	v_cndmask_b32_e64 v97, v194, v97, s[4:5]
	v_cmp_le_i32_e64 s[4:5], v14, v184
	v_add_u32_e32 v14, 0xffffffa3, v0
	v_cmp_le_i32_e64 s[6:7], v14, v184
	v_add_u32_e32 v14, 0xffffff84, v0
	s_nop 0
	v_cndmask_b32_e64 v98, v194, v98, s[6:7]
	v_cmp_le_i32_e64 s[6:7], v14, v184
	v_add_u32_e32 v14, 0xffffffa4, v0
	v_cmp_le_i32_e64 s[8:9], v14, v184
	v_add_u32_e32 v14, 0xffffff89, v0
	s_nop 0
	v_cndmask_b32_e64 v99, v194, v99, s[8:9]
	v_cmp_le_i32_e64 s[8:9], v14, v184
	v_add_u32_e32 v14, 0xffffffa9, v0
	v_cmp_le_i32_e64 s[10:11], v14, v184
	v_add_u32_e32 v14, 0xffffff8a, v0
	s_nop 0
	v_cndmask_b32_e64 v100, v194, v100, s[10:11]
	v_cmp_le_i32_e64 s[10:11], v14, v184
	v_add_u32_e32 v14, 0xffffffaa, v0
	v_cmp_le_i32_e64 s[12:13], v14, v184
	v_add_u32_e32 v14, 0xffffff8b, v0
	s_nop 0
	v_cndmask_b32_e64 v101, v194, v101, s[12:13]
	v_cmp_le_i32_e64 s[12:13], v14, v184
	v_add_u32_e32 v14, 0xffffffab, v0
	v_cmp_le_i32_e64 s[14:15], v14, v184
	v_add_u32_e32 v14, 0xffffff8c, v0
	s_nop 0
	v_cndmask_b32_e64 v102, v194, v102, s[14:15]
	v_cmp_le_i32_e64 s[14:15], v14, v184
	v_add_u32_e32 v14, 0xffffffac, v0
	v_cmp_le_i32_e64 s[16:17], v14, v184
	v_add_u32_e32 v14, 0xffffff91, v0
	s_nop 0
	v_cndmask_b32_e64 v103, v194, v103, s[16:17]
	v_cmp_le_i32_e64 s[16:17], v14, v184
	v_add_u32_e32 v14, 0xffffffb1, v0
	v_cmp_le_i32_e64 s[18:19], v14, v184
	v_add_u32_e32 v14, 0xffffff92, v0
	s_nop 0
	v_cndmask_b32_e64 v104, v194, v104, s[18:19]
	v_cmp_le_i32_e64 s[18:19], v14, v184
	v_add_u32_e32 v14, 0xffffffb2, v0
	v_cmp_le_i32_e64 s[20:21], v14, v184
	v_add_u32_e32 v14, 0xffffff93, v0
	s_nop 0
	v_cndmask_b32_e64 v105, v194, v105, s[20:21]
	v_cmp_le_i32_e64 s[20:21], v14, v184
	v_add_u32_e32 v14, 0xffffffb3, v0
	v_cmp_le_i32_e64 s[22:23], v14, v184
	v_add_u32_e32 v14, 0xffffff94, v0
	s_nop 0
	v_cndmask_b32_e64 v106, v194, v106, s[22:23]
	v_cmp_le_i32_e64 s[22:23], v14, v184
	v_add_u32_e32 v14, 0xffffffb4, v0
	v_cmp_le_i32_e64 s[24:25], v14, v184
	v_add_u32_e32 v14, 0xffffff99, v0
	s_nop 0
	v_cndmask_b32_e64 v107, v194, v107, s[24:25]
	v_cmp_le_i32_e64 s[24:25], v14, v184
	v_add_u32_e32 v14, 0xffffffb9, v0
	v_cmp_le_i32_e64 s[26:27], v14, v184
	v_add_u32_e32 v14, 0xffffff9a, v0
	s_nop 0
	v_cndmask_b32_e64 v108, v194, v108, s[26:27]
	v_cmp_le_i32_e64 s[26:27], v14, v184
	v_add_u32_e32 v14, 0xffffffba, v0
	v_cmp_le_i32_e64 s[28:29], v14, v184
	v_add_u32_e32 v14, 0xffffff9b, v0
	s_nop 0
	v_cndmask_b32_e64 v109, v194, v109, s[28:29]
	v_cmp_le_i32_e64 s[28:29], v14, v184
	v_add_u32_e32 v14, 0xffffffbb, v0
	v_cmp_le_i32_e64 s[30:31], v14, v184
	v_add_u32_e32 v14, 0xffffff9c, v0
	v_add_u32_e32 v0, 0xffffffbc, v0
	v_cndmask_b32_e64 v110, v194, v110, s[30:31]
	v_cmp_le_i32_e64 s[30:31], v14, v184
	v_cmp_gt_i32_e64 s[34:35], v0, v184
	s_and_saveexec_b64 s[48:49], s[34:35]
	v_mov_b32_e32 v111, s59
	s_or_b64 exec, exec, s[48:49]
	v_cndmask_b32_e64 v113, v194, v113, s[2:3]
	v_cndmask_b32_e32 v112, v194, v112, vcc
	v_cndmask_b32_e64 v114, v194, v114, s[4:5]
	v_cndmask_b32_e64 v115, v194, v115, s[6:7]
	v_cndmask_b32_e64 v116, v194, v116, s[8:9]
	v_cndmask_b32_e64 v117, v194, v117, s[10:11]
	v_cndmask_b32_e64 v118, v194, v118, s[12:13]
	v_cndmask_b32_e64 v119, v194, v119, s[14:15]
	v_cndmask_b32_e64 v120, v194, v120, s[16:17]
	v_cndmask_b32_e64 v121, v194, v121, s[18:19]
	v_cndmask_b32_e64 v122, v194, v122, s[20:21]
	v_cndmask_b32_e64 v123, v194, v123, s[22:23]
	v_cndmask_b32_e64 v124, v194, v124, s[24:25]
	v_cndmask_b32_e64 v125, v194, v125, s[26:27]
	v_cndmask_b32_e64 v126, v194, v126, s[28:29]
	v_cndmask_b32_e64 v127, v194, v127, s[30:31]

.LBB0_685:
	s_add_i32 s4, s67, 2
	s_and_b32 s4, s4, 2
	s_mulk_i32 s4, 0x3400
	v_add_u32_e32 v0, s4, v196
	ds_read_b128 v[2:5], v0
	ds_read_b128 v[6:9], v0 offset:6656
	s_mulk_i32 s71, 0x3400
	s_add_i32 s3, s71, 0
	s_xor_b32 s2, s69, 2
	v_add_u32_e32 v96, s3, v192
	s_mulk_i32 s2, 0x2400
	s_waitcnt vmcnt(5)
	ds_write_b128 v96, v[168:171]
	v_add_u32_e32 v96, s3, v185
	s_waitcnt vmcnt(4)
	ds_write_b128 v96, v[164:167] offset:128
	v_add_u32_e32 v96, s2, v193
	s_add_i32 s2, s67, 6
	s_min_i32 s2, s2, s66
	s_mov_b32 s3, s47
	v_add_u32_e32 v96, 0xd000, v96
	s_lshl_b64 s[4:5], s[2:3], 16
	s_lshl_b64 s[2:3], s[2:3], 12
	s_waitcnt vmcnt(3)
	ds_write2_b64 v96, v[160:161], v[162:163] offset1:2
	v_lshl_add_u64 v[98:99], v[186:187], 0, s[4:5]
	v_lshl_add_u64 v[100:101], v[188:189], 0, s[2:3]
	s_lshl_b64 s[2:3], s[46:47], 7
	global_load_dwordx4 v[168:171], v[98:99], off
	global_load_dwordx4 v[164:167], v[100:101], off
	v_lshl_add_u64 v[98:99], v[190:191], 0, s[2:3]
	global_load_dwordx4 v[160:163], v[98:99], off
	s_add_i32 s46, s67, 2
	s_cmp_ge_i32 s67, s65
	s_cbranch_scc1 .LBB0_696
	s_waitcnt lgkmcnt(1)
	v_mfma_f32_32x32x16_bf16 v[112:127], v[2:5], v[128:131], v[48:63]
	ds_read_b128 v[10:13], v0 offset:32
	ds_read_b128 v[202:205], v0 offset:6688
	v_add_f32_e32 v14, 0, v80
	v_add_f32_e32 v14, v81, v14
	v_cvt_pk_bf16_f32 v176, v80, v81
	s_waitcnt lgkmcnt(2)
	v_mfma_f32_32x32x16_bf16 v[96:111], v[6:9], v[128:131], v[48:63]
	v_add_f32_e32 v2, v82, v14
	v_add_f32_e32 v2, v83, v2
	v_add_f32_e32 v14, v84, v2
	v_cvt_pk_bf16_f32 v177, v82, v83
	s_waitcnt lgkmcnt(1)
	v_mfma_f32_32x32x16_bf16 v[112:127], v[10:13], v[132:135], v[112:127]
	ds_read_b128 v[2:5], v0 offset:64
	ds_read_b128 v[6:9], v0 offset:6720
	v_add_f32_e32 v14, v85, v14
	v_add_f32_e32 v14, v86, v14
	v_add_f32_e32 v14, v87, v14
	v_cvt_pk_bf16_f32 v178, v84, v85
	v_cvt_pk_bf16_f32 v179, v86, v87
	s_waitcnt lgkmcnt(2)
	v_mfma_f32_32x32x16_bf16 v[96:111], v[202:205], v[132:135], v[96:111]
	v_add_f32_e32 v10, v88, v14
	v_add_f32_e32 v11, v89, v10
	v_cvt_pk_bf16_f32 v10, v88, v89
	s_waitcnt lgkmcnt(1)
	v_mfma_f32_32x32x16_bf16 v[112:127], v[2:5], v[136:139], v[112:127]
	ds_read_b128 v[80:83], v0 offset:96
	ds_read_b128 v[202:205], v0 offset:6752
	v_add_f32_e32 v11, v90, v11
	v_add_f32_e32 v11, v91, v11
	v_add_f32_e32 v12, v92, v11
	v_cvt_pk_bf16_f32 v11, v90, v91
	s_waitcnt lgkmcnt(2)
	v_mfma_f32_32x32x16_bf16 v[96:111], v[6:9], v[136:139], v[96:111]
	v_add_f32_e32 v2, v93, v12
	v_add_f32_e32 v2, v94, v2
	v_add_f32_e32 v14, v95, v2
	v_cvt_pk_bf16_f32 v12, v92, v93
	v_cvt_pk_bf16_f32 v13, v94, v95
	s_waitcnt lgkmcnt(1)
	v_mfma_f32_32x32x16_bf16 v[112:127], v[80:83], v[140:143], v[112:127]
	ds_read_b128 v[2:5], v0 offset:128
	ds_read_b128 v[206:209], v0 offset:6784
	v_add_f32_e32 v6, v16, v14
	v_add_f32_e32 v7, v17, v6
	v_cvt_pk_bf16_f32 v6, v16, v17
	s_waitcnt lgkmcnt(2)
	v_mfma_f32_32x32x16_bf16 v[96:111], v[202:205], v[140:143], v[96:111]
	v_add_f32_e32 v7, v18, v7
	v_add_f32_e32 v7, v19, v7
	v_add_f32_e32 v8, v20, v7
	v_cvt_pk_bf16_f32 v7, v18, v19
	s_waitcnt lgkmcnt(1)
	v_mfma_f32_32x32x16_bf16 v[112:127], v[2:5], v[144:147], v[112:127]
	ds_read_b128 v[14:17], v0 offset:160
	ds_read_b128 v[80:83], v0 offset:6816
	v_add_f32_e32 v0, v21, v8
	v_add_f32_e32 v0, v22, v0
	v_add_f32_e32 v0, v23, v0
	v_cvt_pk_bf16_f32 v8, v20, v21
	v_cvt_pk_bf16_f32 v9, v22, v23
	s_waitcnt lgkmcnt(2)
	v_mfma_f32_32x32x16_bf16 v[96:111], v[206:209], v[144:147], v[96:111]
	v_add_f32_e32 v0, v24, v0
	v_add_f32_e32 v0, v25, v0
	v_cvt_pk_bf16_f32 v2, v24, v25
	s_waitcnt lgkmcnt(1)
	v_mfma_f32_32x32x16_bf16 v[112:127], v[14:17], v[148:151], v[112:127]
	v_add_f32_e32 v0, v26, v0
	v_add_f32_e32 v0, v27, v0
	v_add_f32_e32 v0, v28, v0
	v_cvt_pk_bf16_f32 v3, v26, v27
	s_waitcnt lgkmcnt(0)
	v_mfma_f32_32x32x16_bf16 v[96:111], v[80:83], v[148:151], v[96:111]
	v_add_f32_e32 v0, v29, v0
	v_add_f32_e32 v0, v30, v0
	v_add_f32_e32 v0, v31, v0
	v_cvt_pk_bf16_f32 v4, v28, v29
	v_cvt_pk_bf16_f32 v5, v30, v31
	s_mul_i32 s4, s69, 0x2400
	v_add_u32_e32 v206, s4, v200
	ds_read_b128 v[16:19], v206 offset:53248
	ds_read_b128 v[202:205], v206 offset:57856
	s_cmp_ge_i32 s70, s65
	v_add_f32_e32 v201, v201, v0
	s_cbranch_scc1 .LBB0_693
	s_cmp_le_i32 s68, s63
	s_cbranch_scc1 .LBB0_691
	v_add_u32_e32 v0, s68, v197
	v_subrev_u32_e32 v15, 31, v0
	v_subrev_u32_e32 v14, 63, v0
	v_cmp_le_i32_e64 s[2:3], v15, v184
	v_cmp_le_i32_e32 vcc, v14, v184
	s_nop 0
	v_cndmask_b32_e64 v96, v194, v96, s[2:3]
	v_cmp_lt_i32_e64 s[2:3], v14, v184
	v_subrev_u32_e32 v14, 30, v0
	v_cmp_le_i32_e64 s[4:5], v14, v184
	v_subrev_u32_e32 v14, 61, v0
	s_nop 0
	v_cndmask_b32_e64 v97, v194, v97, s[4:5]
	v_cmp_le_i32_e64 s[4:5], v14, v184
	v_subrev_u32_e32 v14, 29, v0
	v_cmp_le_i32_e64 s[6:7], v14, v184
	v_subrev_u32_e32 v14, 60, v0
	s_nop 0
	v_cndmask_b32_e64 v98, v194, v98, s[6:7]
	v_cmp_le_i32_e64 s[6:7], v14, v184
	v_subrev_u32_e32 v14, 28, v0
	v_cmp_le_i32_e64 s[8:9], v14, v184
	v_subrev_u32_e32 v14, 55, v0
	s_nop 0
	v_cndmask_b32_e64 v99, v194, v99, s[8:9]
	v_cmp_le_i32_e64 s[8:9], v14, v184
	v_subrev_u32_e32 v14, 23, v0
	v_cmp_le_i32_e64 s[10:11], v14, v184
	v_subrev_u32_e32 v14, 54, v0
	s_nop 0
	v_cndmask_b32_e64 v100, v194, v100, s[10:11]
	v_cmp_le_i32_e64 s[10:11], v14, v184
	v_subrev_u32_e32 v14, 22, v0
	v_cmp_le_i32_e64 s[12:13], v14, v184
	v_subrev_u32_e32 v14, 53, v0
	s_nop 0
	v_cndmask_b32_e64 v101, v194, v101, s[12:13]
	v_cmp_le_i32_e64 s[12:13], v14, v184
	v_subrev_u32_e32 v14, 21, v0
	v_cmp_le_i32_e64 s[14:15], v14, v184
	v_subrev_u32_e32 v14, 52, v0
	s_nop 0
	v_cndmask_b32_e64 v102, v194, v102, s[14:15]
	v_cmp_le_i32_e64 s[14:15], v14, v184
	v_subrev_u32_e32 v14, 20, v0
	v_cmp_le_i32_e64 s[16:17], v14, v184
	v_subrev_u32_e32 v14, 47, v0
	s_nop 0
	v_cndmask_b32_e64 v103, v194, v103, s[16:17]
	v_cmp_le_i32_e64 s[16:17], v14, v184
	v_add_u32_e32 v14, -15, v0
	v_cmp_le_i32_e64 s[18:19], v14, v184
	v_subrev_u32_e32 v14, 46, v0
	s_nop 0
	v_cndmask_b32_e64 v104, v194, v104, s[18:19]
	v_cmp_le_i32_e64 s[18:19], v14, v184
	v_add_u32_e32 v14, -14, v0
	v_cmp_le_i32_e64 s[20:21], v14, v184
	v_subrev_u32_e32 v14, 45, v0
	s_nop 0
	v_cndmask_b32_e64 v105, v194, v105, s[20:21]
	v_cmp_le_i32_e64 s[20:21], v14, v184
	v_add_u32_e32 v14, -13, v0
	v_cmp_le_i32_e64 s[22:23], v14, v184
	v_subrev_u32_e32 v14, 44, v0
	s_nop 0
	v_cndmask_b32_e64 v106, v194, v106, s[22:23]
	v_cmp_le_i32_e64 s[22:23], v14, v184
	v_add_u32_e32 v14, -12, v0
	v_cmp_le_i32_e64 s[24:25], v14, v184
	v_subrev_u32_e32 v14, 39, v0
	s_nop 0
	v_cndmask_b32_e64 v107, v194, v107, s[24:25]
	v_cmp_le_i32_e64 s[24:25], v14, v184
	v_add_u32_e32 v14, -7, v0
	v_cmp_le_i32_e64 s[26:27], v14, v184
	v_subrev_u32_e32 v14, 38, v0
	s_nop 0
	v_cndmask_b32_e64 v108, v194, v108, s[26:27]
	v_cmp_le_i32_e64 s[26:27], v14, v184
	v_add_u32_e32 v14, -6, v0
	v_cmp_le_i32_e64 s[28:29], v14, v184
	v_subrev_u32_e32 v14, 37, v0
	s_nop 0
	v_cndmask_b32_e64 v109, v194, v109, s[28:29]
	v_cmp_le_i32_e64 s[28:29], v14, v184
	v_add_u32_e32 v14, -5, v0
	v_cmp_le_i32_e64 s[30:31], v14, v184
	v_subrev_u32_e32 v14, 36, v0
	v_add_u32_e32 v0, -4, v0
	v_cndmask_b32_e64 v110, v194, v110, s[30:31]
	v_cmp_le_i32_e64 s[30:31], v14, v184
	v_cmp_gt_i32_e64 s[34:35], v0, v184
	s_and_saveexec_b64 s[48:49], s[34:35]
	v_mov_b32_e32 v111, s59
	s_or_b64 exec, exec, s[48:49]
	v_cndmask_b32_e64 v113, v194, v113, s[2:3]
	v_cndmask_b32_e32 v112, v194, v112, vcc
	v_cndmask_b32_e64 v114, v194, v114, s[4:5]
	v_cndmask_b32_e64 v115, v194, v115, s[6:7]
	v_cndmask_b32_e64 v116, v194, v116, s[8:9]
	v_cndmask_b32_e64 v117, v194, v117, s[10:11]
	v_cndmask_b32_e64 v118, v194, v118, s[12:13]
	v_cndmask_b32_e64 v119, v194, v119, s[14:15]
	v_cndmask_b32_e64 v120, v194, v120, s[16:17]
	v_cndmask_b32_e64 v121, v194, v121, s[18:19]
	v_cndmask_b32_e64 v122, v194, v122, s[20:21]
	v_cndmask_b32_e64 v123, v194, v123, s[22:23]
	v_cndmask_b32_e64 v124, v194, v124, s[24:25]
	v_cndmask_b32_e64 v125, v194, v125, s[26:27]
	v_cndmask_b32_e64 v126, v194, v126, s[28:29]
	v_cndmask_b32_e64 v127, v194, v127, s[30:31]
